# the vmcnt(8) and lgkmcnt(0) waits ahead of each k-loop phase barrier merged into one s_waitcnt
# baseline (speedup 1.0000x reference)
; #define PG8_STAGE(bufoff, gbase, voff) do { _Pragma("unroll") for (int _i = 0; _i < 2; ++_i) \
;         __builtin_amdgcn_global_load_lds((const unsigned*)((const char*)(gbase) + (voff)[_i]), (LAS unsigned*)(lds + (bufoff) + ldsw + _i * 8192), 16, 0, 0); } while (0)
; #define PG8_LDA(dst, b, h) do { _Pragma("unroll") for (int m = 0; m < 4; ++m) _Pragma("unroll") for (int k = 0; k < 2; ++k) dst[m][k] = *(const LAS bf16x8*)(lds + PG8_SA(b, h) + aoff + m * 2048 + k * 1024); } while (0)
; #define PG8_LDB(dst, b, h) do { _Pragma("unroll") for (int n = 0; n < 2; ++n) _Pragma("unroll") for (int k = 0; k < 2; ++k) dst[n][k] = *(const LAS bf16x8*)(lds + PG8_SB(b, h) + boff + n * 2048 + k * 1024); } while (0)
; #define PG8_MMA(ai, bj, At, Bt) do { __builtin_amdgcn_s_setprio(1); _Pragma("unroll") for (int m = 0; m < 4; ++m) _Pragma("unroll") for (int n = 0; n < 2; ++n) _Pragma("unroll") for (int k = 0; k < 2; ++k) \
;         acc[ai][bj][m][n] = __builtin_amdgcn_mfma_f32_16x16x32_bf16(Bt[n][k], At[m][k], acc[ai][bj][m][n], 0, 0, 0); __builtin_amdgcn_s_setprio(0); } while (0)
; #define PG8_WAIT_V(n) asm volatile("s_waitcnt vmcnt(" #n ")" ::: "memory")
; #define PG8_BAR __builtin_amdgcn_s_barrier()
; DI void gemm_phase(LAS unsigned char* lds, int ph, unsigned char* ws, unsigned char* wg, int l, const float* pscale, int G, int cidx, int nx) {
;     ...
;         for (int t = 0; t < nt; t += 2) {
;             const bool last = (t == nt - 2);
;             const char* a1 = PG8_KA(t + 1);
;             const char* a2 = last ? nA : PG8_KA(t + 2); const char* b2 = last ? nB : PG8_KB(t + 2);
;             const char* a3 = a2 + kstep; const char* b3 = b2 + kstep;
;             if (zAb != 0 && t != 0 && (t & ntzm) == 0) { unsigned char* wsx = ws; asm volatile("" : "+s"(wsx)); int frx = fr; asm volatile("" : "+v"(frx)); merge_carry(acc, wsx, cur, (t >> lz) - 1, wr, wc, frx, fq); }
;             PG8_LDB(B0, 0, 0); PG8_LDB(B1, 0, 1); PG8_SCHED; PG8_LDA(At, 0, 0); PG8_STAGE(PG8_SA(1, 1), a1 + hstepA, voffA);
;             PG8_WAIT_V(8); PG8_WAIT_L(0); PG8_BAR; PG8_MMA(0, 0, At, B0); PG8_MMA(0, 1, At, B1); PG8_BAR; PG8_SCHED;
;             PG8_LDA(At, 0, 1); PG8_STAGE(PG8_SB(0, 0), b2, voffB); PG8_STAGE(PG8_SB(0, 1), b2 + hstepB, voffB); PG8_STAGE(PG8_SA(0, 0), a2, voffA);
;             PG8_WAIT_V(8); PG8_WAIT_L(0); PG8_BAR; PG8_MMA(1, 0, At, B0); PG8_MMA(1, 1, At, B1); PG8_BAR; PG8_SCHED;
.Lpeel_501:
.Lpeel_500:
	v_add_u32_e32 v80, s91, v173
	s_add_i32 s20, 0, 0x14000
	ds_read_b128 v[132:135], v80
	ds_read_b128 v[136:139], v80 offset:1024
	ds_read_b128 v[142:145], v80 offset:2048
	ds_read_b128 v[158:161], v80 offset:3072
	v_add_u32_e32 v80, s20, v173
	ds_read_b128 v[176:179], v80
	ds_read_b128 v[180:183], v80 offset:1024
	ds_read_b128 v[184:187], v80 offset:2048
	ds_read_b128 v[188:191], v80 offset:3072
	ds_read_b128 v[192:195], v174
	ds_read_b128 v[196:199], v174 offset:1024
	ds_read_b128 v[200:203], v174 offset:2048
	ds_read_b128 v[204:207], v174 offset:3072
	ds_read_b128 v[208:211], v174 offset:4096
	ds_read_b128 v[212:215], v174 offset:5120
	ds_read_b128 v[216:219], v174 offset:6144
	ds_read_b128 v[220:223], v174 offset:7168
	s_add_i32 m0, s79, 0xc000
	s_add_i32 s12, s38, 1
	s_lshr_b32 s18, s12, s76
	s_mul_i32 s19, s53, s18
	s_mul_hi_u32 s21, s52, s18
	s_add_i32 s21, s21, s19
	s_mul_i32 s18, s52, s18
	s_add_u32 s18, s42, s18
	s_addc_u32 s19, s43, s21
	s_and_b32 s12, s12, s83
	s_lshl_b32 s12, s12, 7
	s_add_u32 s12, s18, s12
	s_addc_u32 s19, s19, 0
	s_add_u32 s18, s12, s7
	s_addc_u32 s19, s19, 0
	global_load_lds_dwordx4 v150, s[18:19]
	s_add_i32 m0, s79, 0xe000
	s_nop 0
	global_load_lds_dwordx4 v154, s[18:19]
	s_waitcnt vmcnt(8) lgkmcnt(0)
	s_barrier
	s_setprio 1
	v_mfma_f32_16x16x32_bf16 v[128:131], v[132:135], v[192:195], 0
	s_add_i32 s0, s38, 2
	v_mfma_f32_16x16x32_bf16 v[124:127], v[142:145], v[192:195], 0
	s_lshr_b32 s1, s0, s76
	v_mfma_f32_16x16x32_bf16 v[112:115], v[132:135], v[200:203], 0
	s_mul_i32 s12, s53, s1
	v_mfma_f32_16x16x32_bf16 v[108:111], v[142:145], v[200:203], 0
	s_mul_hi_u32 s18, s52, s1
	v_mfma_f32_16x16x32_bf16 v[96:99], v[132:135], v[208:211], 0
	s_add_i32 s18, s18, s12
	v_mfma_f32_16x16x32_bf16 v[92:95], v[142:145], v[208:211], 0
	s_mul_i32 s12, s52, s1
	v_mfma_f32_16x16x32_bf16 v[76:79], v[132:135], v[216:219], 0
	s_and_b32 s0, s0, s83
	v_mfma_f32_16x16x32_bf16 v[72:75], v[142:145], v[216:219], 0
	s_lshl_b32 s0, s0, 7
	v_mfma_f32_16x16x32_bf16 v[128:131], v[136:139], v[196:199], v[128:131]
	s_mul_i32 s19, s49, s1
	v_mfma_f32_16x16x32_bf16 v[124:127], v[158:161], v[196:199], v[124:127]
	s_mul_hi_u32 s21, s48, s1
	v_mfma_f32_16x16x32_bf16 v[112:115], v[136:139], v[204:207], v[112:115]
	s_add_i32 s21, s21, s19
	v_mfma_f32_16x16x32_bf16 v[108:111], v[158:161], v[204:207], v[108:111]
	s_mul_i32 s19, s48, s1
	v_mfma_f32_16x16x32_bf16 v[96:99], v[136:139], v[212:215], v[96:99]
	s_add_u32 s12, s42, s12
	v_mfma_f32_16x16x32_bf16 v[92:95], v[158:161], v[212:215], v[92:95]
	s_addc_u32 s18, s43, s18
	v_mfma_f32_16x16x32_bf16 v[76:79], v[136:139], v[220:223], v[76:79]
	s_add_u32 s12, s12, s0
	v_mfma_f32_16x16x32_bf16 v[72:75], v[158:161], v[220:223], v[72:75]
	s_addc_u32 s18, s18, 0
	v_mfma_f32_16x16x32_bf16 v[120:123], v[176:179], v[192:195], 0
	s_add_u32 s19, s40, s19
	v_mfma_f32_16x16x32_bf16 v[116:119], v[184:187], v[192:195], 0
	s_addc_u32 s21, s41, s21
	v_mfma_f32_16x16x32_bf16 v[104:107], v[176:179], v[200:203], 0
	s_add_u32 s19, s19, s0
	v_mfma_f32_16x16x32_bf16 v[100:103], v[184:187], v[200:203], 0
	s_addc_u32 s21, s21, 0
	v_mfma_f32_16x16x32_bf16 v[88:91], v[176:179], v[208:211], 0
	s_cmp_eq_u32 s96, s38
	v_mfma_f32_16x16x32_bf16 v[82:85], v[184:187], v[208:211], 0
	s_cselect_b32 s0, s60, s12
	v_mfma_f32_16x16x32_bf16 v[68:71], v[176:179], v[216:219], 0
	s_cselect_b32 s1, s61, s18
	v_mfma_f32_16x16x32_bf16 v[64:67], v[184:187], v[216:219], 0
	s_cselect_b32 s64, s62, s19
	v_mfma_f32_16x16x32_bf16 v[120:123], v[180:183], v[196:199], v[120:123]
	s_cselect_b32 s65, s63, s21
	v_mfma_f32_16x16x32_bf16 v[116:119], v[188:191], v[196:199], v[116:119]
	v_mfma_f32_16x16x32_bf16 v[104:107], v[180:183], v[204:207], v[104:107]
	v_mfma_f32_16x16x32_bf16 v[100:103], v[188:191], v[204:207], v[100:103]
	v_mfma_f32_16x16x32_bf16 v[88:91], v[180:183], v[212:215], v[88:91]
	v_mfma_f32_16x16x32_bf16 v[82:85], v[188:191], v[212:215], v[82:85]
	v_mfma_f32_16x16x32_bf16 v[68:71], v[180:183], v[220:223], v[68:71]
	v_mfma_f32_16x16x32_bf16 v[64:67], v[188:191], v[220:223], v[64:67]
	s_setprio 0
	s_barrier
	s_add_i32 s12, s91, s78
	s_mov_b32 m0, s12
	ds_read_b128 v[192:195], v174 offset:16384
	ds_read_b128 v[196:199], v174 offset:17408
	ds_read_b128 v[200:203], v174 offset:18432
	ds_read_b128 v[204:207], v174 offset:19456
	ds_read_b128 v[208:211], v174 offset:20480
	ds_read_b128 v[212:215], v174 offset:21504
	ds_read_b128 v[216:219], v174 offset:22528
	ds_read_b128 v[220:223], v174 offset:23552
	global_load_lds_dwordx4 v152, s[64:65]
	s_add_i32 m0, s12, 0x2000
	s_add_u32 s18, s64, s77
	s_addc_u32 s19, s65, 0
	s_add_i32 s12, s20, s78
	global_load_lds_dwordx4 v156, s[64:65]
	s_mov_b32 m0, s12
	s_nop 0
	global_load_lds_dwordx4 v152, s[18:19]
	s_add_i32 m0, s12, 0x2000
	s_nop 0
	global_load_lds_dwordx4 v156, s[18:19]
	s_mov_b32 m0, s79
	s_nop 0
	global_load_lds_dwordx4 v150, s[0:1]
	s_mov_b32 m0, s80
	s_nop 0
	global_load_lds_dwordx4 v154, s[0:1]
	s_waitcnt vmcnt(8) lgkmcnt(0)
	s_barrier
; #define PG8_STAGE(bufoff, gbase, voff) do { _Pragma("unroll") for (int _i = 0; _i < 2; ++_i) \
;         __builtin_amdgcn_global_load_lds((const unsigned*)((const char*)(gbase) + (voff)[_i]), (LAS unsigned*)(lds + (bufoff) + ldsw + _i * 8192), 16, 0, 0); } while (0)
; #define PG8_LDA(dst, b, h) do { _Pragma("unroll") for (int m = 0; m < 4; ++m) _Pragma("unroll") for (int k = 0; k < 2; ++k) dst[m][k] = *(const LAS bf16x8*)(lds + PG8_SA(b, h) + aoff + m * 2048 + k * 1024); } while (0)
; #define PG8_LDB(dst, b, h) do { _Pragma("unroll") for (int n = 0; n < 2; ++n) _Pragma("unroll") for (int k = 0; k < 2; ++k) dst[n][k] = *(const LAS bf16x8*)(lds + PG8_SB(b, h) + boff + n * 2048 + k * 1024); } while (0)
; #define PG8_MMA(ai, bj, At, Bt) do { __builtin_amdgcn_s_setprio(1); _Pragma("unroll") for (int m = 0; m < 4; ++m) _Pragma("unroll") for (int n = 0; n < 2; ++n) _Pragma("unroll") for (int k = 0; k < 2; ++k) \
;         acc[ai][bj][m][n] = __builtin_amdgcn_mfma_f32_16x16x32_bf16(Bt[n][k], At[m][k], acc[ai][bj][m][n], 0, 0, 0); __builtin_amdgcn_s_setprio(0); } while (0)
; #define PG8_WAIT_V(n) asm volatile("s_waitcnt vmcnt(" #n ")" ::: "memory")
; #define PG8_WAIT_L(n) asm volatile("s_waitcnt lgkmcnt(" #n ")" ::: "memory")
; #define PG8_BAR __builtin_amdgcn_s_barrier()
; #define PG8_SCHED __builtin_amdgcn_sched_barrier(0)
; DI void gemm_phase(LAS unsigned char* lds, int ph, unsigned char* ws, unsigned char* wg, int l, const float* pscale, int G, int cidx, int nx) {
;     ...
;             PG8_WAIT_V(8); PG8_WAIT_L(0); PG8_BAR; PG8_MMA(1, 0, At, B0); PG8_MMA(1, 1, At, B1); PG8_BAR; PG8_SCHED;
;             PG8_LDB(B0, 1, 0); PG8_LDB(B1, 1, 1); PG8_SCHED; PG8_LDA(At, 1, 0); PG8_STAGE(PG8_SA(0, 1), a2 + hstepA, voffA);
;             PG8_WAIT_V(8); PG8_WAIT_L(0); PG8_BAR; PG8_MMA(0, 0, At, B0); PG8_MMA(0, 1, At, B1); PG8_BAR; PG8_SCHED;
	s_setprio 1
	v_mfma_f32_16x16x32_bf16 v[60:63], v[132:135], v[192:195], 0
	v_mfma_f32_16x16x32_bf16 v[56:59], v[142:145], v[192:195], 0
	v_mfma_f32_16x16x32_bf16 v[44:47], v[132:135], v[200:203], 0
	v_mfma_f32_16x16x32_bf16 v[40:43], v[142:145], v[200:203], 0
	v_mfma_f32_16x16x32_bf16 v[28:31], v[132:135], v[208:211], 0
	v_mfma_f32_16x16x32_bf16 v[24:27], v[142:145], v[208:211], 0
	v_mfma_f32_16x16x32_bf16 v[12:15], v[132:135], v[216:219], 0
	v_mfma_f32_16x16x32_bf16 v[8:11], v[142:145], v[216:219], 0
	v_mfma_f32_16x16x32_bf16 v[60:63], v[136:139], v[196:199], v[60:63]
	v_mfma_f32_16x16x32_bf16 v[56:59], v[158:161], v[196:199], v[56:59]
	v_mfma_f32_16x16x32_bf16 v[44:47], v[136:139], v[204:207], v[44:47]
	v_mfma_f32_16x16x32_bf16 v[40:43], v[158:161], v[204:207], v[40:43]
	v_mfma_f32_16x16x32_bf16 v[28:31], v[136:139], v[212:215], v[28:31]
	v_mfma_f32_16x16x32_bf16 v[24:27], v[158:161], v[212:215], v[24:27]
	v_mfma_f32_16x16x32_bf16 v[12:15], v[136:139], v[220:223], v[12:15]
	v_mfma_f32_16x16x32_bf16 v[8:11], v[158:161], v[220:223], v[8:11]
	v_mfma_f32_16x16x32_bf16 v[52:55], v[176:179], v[192:195], 0
	v_mfma_f32_16x16x32_bf16 v[48:51], v[184:187], v[192:195], 0
	v_mfma_f32_16x16x32_bf16 v[36:39], v[176:179], v[200:203], 0
	v_mfma_f32_16x16x32_bf16 v[32:35], v[184:187], v[200:203], 0
	v_mfma_f32_16x16x32_bf16 v[20:23], v[176:179], v[208:211], 0
	v_mfma_f32_16x16x32_bf16 v[16:19], v[184:187], v[208:211], 0
	v_mfma_f32_16x16x32_bf16 v[4:7], v[176:179], v[216:219], 0
	v_mfma_f32_16x16x32_bf16 v[0:3], v[184:187], v[216:219], 0
	v_mfma_f32_16x16x32_bf16 v[52:55], v[180:183], v[196:199], v[52:55]
	v_mfma_f32_16x16x32_bf16 v[48:51], v[188:191], v[196:199], v[48:51]
	v_mfma_f32_16x16x32_bf16 v[36:39], v[180:183], v[204:207], v[36:39]
	v_mfma_f32_16x16x32_bf16 v[32:35], v[188:191], v[204:207], v[32:35]
	v_mfma_f32_16x16x32_bf16 v[20:23], v[180:183], v[212:215], v[20:23]
	v_mfma_f32_16x16x32_bf16 v[16:19], v[188:191], v[212:215], v[16:19]
	v_mfma_f32_16x16x32_bf16 v[4:7], v[180:183], v[220:223], v[4:7]
	v_mfma_f32_16x16x32_bf16 v[0:3], v[188:191], v[220:223], v[0:3]
	s_setprio 0
	s_barrier
	s_add_i32 s12, 0, 0x18000
	v_add_u32_e32 v80, s12, v173
	s_add_i32 s18, 0, 0x1c000
	ds_read_b128 v[132:135], v80
	ds_read_b128 v[136:139], v80 offset:1024
	ds_read_b128 v[142:145], v80 offset:2048
	ds_read_b128 v[158:161], v80 offset:3072
	v_add_u32_e32 v80, s18, v173
	ds_read_b128 v[176:179], v80
	ds_read_b128 v[180:183], v80 offset:1024
	ds_read_b128 v[184:187], v80 offset:2048
	ds_read_b128 v[188:191], v80 offset:3072
	s_add_u32 s0, s0, s7
	s_addc_u32 s1, s1, 0
	s_mov_b32 m0, s81
	ds_read_b128 v[192:195], v174 offset:32768
	ds_read_b128 v[196:199], v174 offset:33792
	ds_read_b128 v[200:203], v174 offset:34816
	ds_read_b128 v[204:207], v174 offset:35840
	ds_read_b128 v[208:211], v174 offset:36864
	ds_read_b128 v[212:215], v174 offset:37888
	ds_read_b128 v[216:219], v174 offset:38912
	ds_read_b128 v[220:223], v174 offset:39936
	global_load_lds_dwordx4 v150, s[0:1]
	s_mov_b32 m0, s82
	s_nop 0
	global_load_lds_dwordx4 v154, s[0:1]
	s_waitcnt vmcnt(8) lgkmcnt(0)
	s_barrier
	s_setprio 1
	v_mfma_f32_16x16x32_bf16 v[128:131], v[132:135], v[192:195], v[128:131]
	s_sub_u32 s20, s0, s7
	v_mfma_f32_16x16x32_bf16 v[124:127], v[142:145], v[192:195], v[124:127]
	s_subb_u32 s21, s1, 0
	v_mfma_f32_16x16x32_bf16 v[112:115], v[132:135], v[200:203], v[112:115]
	s_add_u32 s20, s20, s4
	v_mfma_f32_16x16x32_bf16 v[108:111], v[142:145], v[200:203], v[108:111]
	s_addc_u32 s21, s21, s5
	v_mfma_f32_16x16x32_bf16 v[96:99], v[132:135], v[208:211], v[96:99]
	s_add_u32 s0, s64, s4
	v_mfma_f32_16x16x32_bf16 v[92:95], v[142:145], v[208:211], v[92:95]
	s_addc_u32 s1, s65, s5
	v_mfma_f32_16x16x32_bf16 v[76:79], v[132:135], v[216:219], v[76:79]
	v_mfma_f32_16x16x32_bf16 v[72:75], v[142:145], v[216:219], v[72:75]
	v_mfma_f32_16x16x32_bf16 v[128:131], v[136:139], v[196:199], v[128:131]
	v_mfma_f32_16x16x32_bf16 v[124:127], v[158:161], v[196:199], v[124:127]
	v_mfma_f32_16x16x32_bf16 v[112:115], v[136:139], v[204:207], v[112:115]
	v_mfma_f32_16x16x32_bf16 v[108:111], v[158:161], v[204:207], v[108:111]
	v_mfma_f32_16x16x32_bf16 v[96:99], v[136:139], v[212:215], v[96:99]
	v_mfma_f32_16x16x32_bf16 v[92:95], v[158:161], v[212:215], v[92:95]
	v_mfma_f32_16x16x32_bf16 v[76:79], v[136:139], v[220:223], v[76:79]
	v_mfma_f32_16x16x32_bf16 v[72:75], v[158:161], v[220:223], v[72:75]
	v_mfma_f32_16x16x32_bf16 v[120:123], v[176:179], v[192:195], v[120:123]
	v_mfma_f32_16x16x32_bf16 v[116:119], v[184:187], v[192:195], v[116:119]
	v_mfma_f32_16x16x32_bf16 v[104:107], v[176:179], v[200:203], v[104:107]
	v_mfma_f32_16x16x32_bf16 v[100:103], v[184:187], v[200:203], v[100:103]
	v_mfma_f32_16x16x32_bf16 v[86:89], v[176:179], v[208:211], v[88:91]
	v_mfma_f32_16x16x32_bf16 v[82:85], v[184:187], v[208:211], v[82:85]
	v_mfma_f32_16x16x32_bf16 v[68:71], v[176:179], v[216:219], v[68:71]
	v_mfma_f32_16x16x32_bf16 v[64:67], v[184:187], v[216:219], v[64:67]
	v_mfma_f32_16x16x32_bf16 v[120:123], v[180:183], v[196:199], v[120:123]
	v_mfma_f32_16x16x32_bf16 v[116:119], v[188:191], v[196:199], v[116:119]
	v_mfma_f32_16x16x32_bf16 v[104:107], v[180:183], v[204:207], v[104:107]
	v_mfma_f32_16x16x32_bf16 v[100:103], v[188:191], v[204:207], v[100:103]
	v_mfma_f32_16x16x32_bf16 v[88:91], v[180:183], v[212:215], v[86:89]
	v_mfma_f32_16x16x32_bf16 v[84:87], v[188:191], v[212:215], v[82:85]
	v_mfma_f32_16x16x32_bf16 v[68:71], v[180:183], v[220:223], v[68:71]
	v_mfma_f32_16x16x32_bf16 v[64:67], v[188:191], v[220:223], v[64:67]
	s_setprio 0
	s_barrier
; #define PG8_STAGE(bufoff, gbase, voff) do { _Pragma("unroll") for (int _i = 0; _i < 2; ++_i) \
;         __builtin_amdgcn_global_load_lds((const unsigned*)((const char*)(gbase) + (voff)[_i]), (LAS unsigned*)(lds + (bufoff) + ldsw + _i * 8192), 16, 0, 0); } while (0)
; #define PG8_LDA(dst, b, h) do { _Pragma("unroll") for (int m = 0; m < 4; ++m) _Pragma("unroll") for (int k = 0; k < 2; ++k) dst[m][k] = *(const LAS bf16x8*)(lds + PG8_SA(b, h) + aoff + m * 2048 + k * 1024); } while (0)
; #define PG8_LDB(dst, b, h) do { _Pragma("unroll") for (int n = 0; n < 2; ++n) _Pragma("unroll") for (int k = 0; k < 2; ++k) dst[n][k] = *(const LAS bf16x8*)(lds + PG8_SB(b, h) + boff + n * 2048 + k * 1024); } while (0)
; #define PG8_MMA(ai, bj, At, Bt) do { __builtin_amdgcn_s_setprio(1); _Pragma("unroll") for (int m = 0; m < 4; ++m) _Pragma("unroll") for (int n = 0; n < 2; ++n) _Pragma("unroll") for (int k = 0; k < 2; ++k) \
;         acc[ai][bj][m][n] = __builtin_amdgcn_mfma_f32_16x16x32_bf16(Bt[n][k], At[m][k], acc[ai][bj][m][n], 0, 0, 0); __builtin_amdgcn_s_setprio(0); } while (0)
; #define PG8_WAIT_V(n) asm volatile("s_waitcnt vmcnt(" #n ")" ::: "memory")
; #define PG8_BAR __builtin_amdgcn_s_barrier()
; DI void gemm_phase(LAS unsigned char* lds, int ph, unsigned char* ws, unsigned char* wg, int l, const float* pscale, int G, int cidx, int nx) {
;     ...
;         for (int t = 0; t < nt; t += 2) {
;             const bool last = (t == nt - 2);
;             const char* a1 = PG8_KA(t + 1);
;             const char* a2 = last ? nA : PG8_KA(t + 2); const char* b2 = last ? nB : PG8_KB(t + 2);
;             const char* a3 = a2 + kstep; const char* b3 = b2 + kstep;
;             if (zAb != 0 && t != 0 && (t & ntzm) == 0) { unsigned char* wsx = ws; asm volatile("" : "+s"(wsx)); int frx = fr; asm volatile("" : "+v"(frx)); merge_carry(acc, wsx, cur, (t >> lz) - 1, wr, wc, frx, fq); }
;             PG8_LDB(B0, 0, 0); PG8_LDB(B1, 0, 1); PG8_SCHED; PG8_LDA(At, 0, 0); PG8_STAGE(PG8_SA(1, 1), a1 + hstepA, voffA);
;             PG8_WAIT_V(8); PG8_WAIT_L(0); PG8_BAR; PG8_MMA(0, 0, At, B0); PG8_MMA(0, 1, At, B1); PG8_BAR; PG8_SCHED;
;     ...
;             PG8_LDA(At, 1, 1); PG8_STAGE(PG8_SB(1, 0), b3, voffB); PG8_STAGE(PG8_SB(1, 1), b3 + hstepB, voffB); PG8_STAGE(PG8_SA(1, 0), a3, voffA);
;             PG8_WAIT_V(8); PG8_WAIT_L(0); PG8_BAR; PG8_MMA(1, 0, At, B0); PG8_MMA(1, 1, At, B1); PG8_BAR; PG8_SCHED;
	s_add_i32 s19, s12, s78
	s_mov_b32 m0, s19
	ds_read_b128 v[192:195], v174 offset:49152
	ds_read_b128 v[196:199], v174 offset:50176
	ds_read_b128 v[200:203], v174 offset:51200
	ds_read_b128 v[204:207], v174 offset:52224
	ds_read_b128 v[208:211], v174 offset:53248
	ds_read_b128 v[212:215], v174 offset:54272
	ds_read_b128 v[216:219], v174 offset:55296
	ds_read_b128 v[220:223], v174 offset:56320
	global_load_lds_dwordx4 v152, s[0:1]
	s_add_i32 m0, s19, 0x2000
	s_add_i32 s19, s18, s78
	global_load_lds_dwordx4 v156, s[0:1]
	s_add_u32 s0, s0, s77
	s_addc_u32 s1, s1, 0
	s_mov_b32 m0, s19
	s_nop 0
	global_load_lds_dwordx4 v152, s[0:1]
	s_add_i32 m0, s19, 0x2000
	s_nop 0
	global_load_lds_dwordx4 v156, s[0:1]
	s_mov_b32 m0, s93
	s_nop 0
	global_load_lds_dwordx4 v150, s[20:21]
	s_mov_b32 m0, s94
	s_nop 0
	global_load_lds_dwordx4 v154, s[20:21]
	s_waitcnt vmcnt(8) lgkmcnt(0)
	s_barrier
	s_setprio 1
	v_mfma_f32_16x16x32_bf16 v[60:63], v[132:135], v[192:195], v[60:63]
	s_add_i32 s38, s38, 2
	v_mfma_f32_16x16x32_bf16 v[56:59], v[142:145], v[192:195], v[56:59]
	s_cmp_ge_u32 s38, s75
	v_mfma_f32_16x16x32_bf16 v[44:47], v[132:135], v[200:203], v[44:47]
	v_mfma_f32_16x16x32_bf16 v[40:43], v[142:145], v[200:203], v[40:43]
	v_mfma_f32_16x16x32_bf16 v[28:31], v[132:135], v[208:211], v[28:31]
	v_mfma_f32_16x16x32_bf16 v[24:27], v[142:145], v[208:211], v[24:27]
	v_mfma_f32_16x16x32_bf16 v[12:15], v[132:135], v[216:219], v[12:15]
	v_mfma_f32_16x16x32_bf16 v[8:11], v[142:145], v[216:219], v[8:11]
	v_mfma_f32_16x16x32_bf16 v[60:63], v[136:139], v[196:199], v[60:63]
	v_mfma_f32_16x16x32_bf16 v[56:59], v[158:161], v[196:199], v[56:59]
	v_mfma_f32_16x16x32_bf16 v[44:47], v[136:139], v[204:207], v[44:47]
	v_mfma_f32_16x16x32_bf16 v[40:43], v[158:161], v[204:207], v[40:43]
	v_mfma_f32_16x16x32_bf16 v[28:31], v[136:139], v[212:215], v[28:31]
	v_mfma_f32_16x16x32_bf16 v[24:27], v[158:161], v[212:215], v[24:27]
	v_mfma_f32_16x16x32_bf16 v[12:15], v[136:139], v[220:223], v[12:15]
	v_mfma_f32_16x16x32_bf16 v[8:11], v[158:161], v[220:223], v[8:11]
	v_mfma_f32_16x16x32_bf16 v[52:55], v[176:179], v[192:195], v[52:55]
	v_mfma_f32_16x16x32_bf16 v[48:51], v[184:187], v[192:195], v[48:51]
	v_mfma_f32_16x16x32_bf16 v[36:39], v[176:179], v[200:203], v[36:39]
	v_mfma_f32_16x16x32_bf16 v[32:35], v[184:187], v[200:203], v[32:35]
	v_mfma_f32_16x16x32_bf16 v[20:23], v[176:179], v[208:211], v[20:23]
	v_mfma_f32_16x16x32_bf16 v[16:19], v[184:187], v[208:211], v[16:19]
	v_mfma_f32_16x16x32_bf16 v[4:7], v[176:179], v[216:219], v[4:7]
	v_mfma_f32_16x16x32_bf16 v[0:3], v[184:187], v[216:219], v[0:3]
	v_mfma_f32_16x16x32_bf16 v[52:55], v[180:183], v[196:199], v[52:55]
	v_mfma_f32_16x16x32_bf16 v[48:51], v[188:191], v[196:199], v[48:51]
	v_mfma_f32_16x16x32_bf16 v[36:39], v[180:183], v[204:207], v[36:39]
	v_mfma_f32_16x16x32_bf16 v[32:35], v[188:191], v[204:207], v[32:35]
	v_mfma_f32_16x16x32_bf16 v[20:23], v[180:183], v[212:215], v[20:23]
	v_mfma_f32_16x16x32_bf16 v[16:19], v[188:191], v[212:215], v[16:19]
	v_mfma_f32_16x16x32_bf16 v[4:7], v[180:183], v[220:223], v[4:7]
	v_mfma_f32_16x16x32_bf16 v[0:3], v[188:191], v[220:223], v[0:3]
	s_setprio 0
	s_barrier
	s_cbranch_scc1 .LBB0_507
	s_branch .LBB0_501
.LBB0_500:
	v_add_u32_e32 v80, s91, v173
	s_add_i32 s20, 0, 0x14000
	ds_read_b128 v[132:135], v80
	ds_read_b128 v[136:139], v80 offset:1024
	ds_read_b128 v[142:145], v80 offset:2048
	ds_read_b128 v[158:161], v80 offset:3072
	v_add_u32_e32 v80, s20, v173
	ds_read_b128 v[176:179], v80
	ds_read_b128 v[180:183], v80 offset:1024
	ds_read_b128 v[184:187], v80 offset:2048
	ds_read_b128 v[188:191], v80 offset:3072
	ds_read_b128 v[192:195], v174
	ds_read_b128 v[196:199], v174 offset:1024
	ds_read_b128 v[200:203], v174 offset:2048
	ds_read_b128 v[204:207], v174 offset:3072
	ds_read_b128 v[208:211], v174 offset:4096
	ds_read_b128 v[212:215], v174 offset:5120
	ds_read_b128 v[216:219], v174 offset:6144
	ds_read_b128 v[220:223], v174 offset:7168
	s_add_i32 m0, s79, 0xc000
	s_add_i32 s12, s38, 1
	s_lshr_b32 s18, s12, s76
	s_mul_i32 s19, s53, s18
	s_mul_hi_u32 s21, s52, s18
	s_add_i32 s21, s21, s19
	s_mul_i32 s18, s52, s18
	s_add_u32 s18, s42, s18
	s_addc_u32 s19, s43, s21
	s_and_b32 s12, s12, s83
	s_lshl_b32 s12, s12, 7
	s_add_u32 s12, s18, s12
	s_addc_u32 s19, s19, 0
	s_add_u32 s18, s12, s7
	s_addc_u32 s19, s19, 0
	global_load_lds_dwordx4 v150, s[18:19]
	s_add_i32 m0, s79, 0xe000
	s_nop 0
	global_load_lds_dwordx4 v154, s[18:19]
	s_waitcnt vmcnt(8) lgkmcnt(0)
	s_barrier
; #define PG8_STAGE(bufoff, gbase, voff) do { _Pragma("unroll") for (int _i = 0; _i < 2; ++_i) \
;         __builtin_amdgcn_global_load_lds((const unsigned*)((const char*)(gbase) + (voff)[_i]), (LAS unsigned*)(lds + (bufoff) + ldsw + _i * 8192), 16, 0, 0); } while (0)
; #define PG8_LDA(dst, b, h) do { _Pragma("unroll") for (int m = 0; m < 4; ++m) _Pragma("unroll") for (int k = 0; k < 2; ++k) dst[m][k] = *(const LAS bf16x8*)(lds + PG8_SA(b, h) + aoff + m * 2048 + k * 1024); } while (0)
; #define PG8_LDB(dst, b, h) do { _Pragma("unroll") for (int n = 0; n < 2; ++n) _Pragma("unroll") for (int k = 0; k < 2; ++k) dst[n][k] = *(const LAS bf16x8*)(lds + PG8_SB(b, h) + boff + n * 2048 + k * 1024); } while (0)
; #define PG8_MMA(ai, bj, At, Bt) do { __builtin_amdgcn_s_setprio(1); _Pragma("unroll") for (int m = 0; m < 4; ++m) _Pragma("unroll") for (int n = 0; n < 2; ++n) _Pragma("unroll") for (int k = 0; k < 2; ++k) \
;         acc[ai][bj][m][n] = __builtin_amdgcn_mfma_f32_16x16x32_bf16(Bt[n][k], At[m][k], acc[ai][bj][m][n], 0, 0, 0); __builtin_amdgcn_s_setprio(0); } while (0)
; #define PG8_WAIT_V(n) asm volatile("s_waitcnt vmcnt(" #n ")" ::: "memory")
; #define PG8_WAIT_L(n) asm volatile("s_waitcnt lgkmcnt(" #n ")" ::: "memory")
; #define PG8_BAR __builtin_amdgcn_s_barrier()
; #define PG8_SCHED __builtin_amdgcn_sched_barrier(0)
; DI void gemm_phase(LAS unsigned char* lds, int ph, unsigned char* ws, unsigned char* wg, int l, const float* pscale, int G, int cidx, int nx) {
;     ...
;             PG8_WAIT_V(8); PG8_WAIT_L(0); PG8_BAR; PG8_MMA(0, 0, At, B0); PG8_MMA(0, 1, At, B1); PG8_BAR; PG8_SCHED;
;             PG8_LDA(At, 0, 1); PG8_STAGE(PG8_SB(0, 0), b2, voffB); PG8_STAGE(PG8_SB(0, 1), b2 + hstepB, voffB); PG8_STAGE(PG8_SA(0, 0), a2, voffA);
;             PG8_WAIT_V(8); PG8_WAIT_L(0); PG8_BAR; PG8_MMA(1, 0, At, B0); PG8_MMA(1, 1, At, B1); PG8_BAR; PG8_SCHED;
;             PG8_LDB(B0, 1, 0); PG8_LDB(B1, 1, 1); PG8_SCHED; PG8_LDA(At, 1, 0); PG8_STAGE(PG8_SA(0, 1), a2 + hstepA, voffA);
;             PG8_WAIT_V(8); PG8_WAIT_L(0); PG8_BAR; PG8_MMA(0, 0, At, B0); PG8_MMA(0, 1, At, B1); PG8_BAR; PG8_SCHED;
	s_setprio 1
	v_mfma_f32_16x16x32_bf16 v[128:131], v[132:135], v[192:195], v[128:131]
	s_add_i32 s0, s38, 2
	v_mfma_f32_16x16x32_bf16 v[124:127], v[142:145], v[192:195], v[124:127]
	s_lshr_b32 s1, s0, s76
	v_mfma_f32_16x16x32_bf16 v[112:115], v[132:135], v[200:203], v[112:115]
	s_mul_i32 s12, s53, s1
	v_mfma_f32_16x16x32_bf16 v[108:111], v[142:145], v[200:203], v[108:111]
	s_mul_hi_u32 s18, s52, s1
	v_mfma_f32_16x16x32_bf16 v[96:99], v[132:135], v[208:211], v[96:99]
	s_add_i32 s18, s18, s12
	v_mfma_f32_16x16x32_bf16 v[92:95], v[142:145], v[208:211], v[92:95]
	s_mul_i32 s12, s52, s1
	v_mfma_f32_16x16x32_bf16 v[76:79], v[132:135], v[216:219], v[76:79]
	s_and_b32 s0, s0, s83
	v_mfma_f32_16x16x32_bf16 v[72:75], v[142:145], v[216:219], v[72:75]
	s_lshl_b32 s0, s0, 7
	v_mfma_f32_16x16x32_bf16 v[128:131], v[136:139], v[196:199], v[128:131]
	s_mul_i32 s19, s49, s1
	v_mfma_f32_16x16x32_bf16 v[124:127], v[158:161], v[196:199], v[124:127]
	s_mul_hi_u32 s21, s48, s1
	v_mfma_f32_16x16x32_bf16 v[112:115], v[136:139], v[204:207], v[112:115]
	s_add_i32 s21, s21, s19
	v_mfma_f32_16x16x32_bf16 v[108:111], v[158:161], v[204:207], v[108:111]
	s_mul_i32 s19, s48, s1
	v_mfma_f32_16x16x32_bf16 v[96:99], v[136:139], v[212:215], v[96:99]
	s_add_u32 s12, s42, s12
	v_mfma_f32_16x16x32_bf16 v[92:95], v[158:161], v[212:215], v[92:95]
	s_addc_u32 s18, s43, s18
	v_mfma_f32_16x16x32_bf16 v[76:79], v[136:139], v[220:223], v[76:79]
	s_add_u32 s12, s12, s0
	v_mfma_f32_16x16x32_bf16 v[72:75], v[158:161], v[220:223], v[72:75]
	s_addc_u32 s18, s18, 0
	v_mfma_f32_16x16x32_bf16 v[120:123], v[176:179], v[192:195], v[120:123]
	s_add_u32 s19, s40, s19
	v_mfma_f32_16x16x32_bf16 v[116:119], v[184:187], v[192:195], v[116:119]
	s_addc_u32 s21, s41, s21
	v_mfma_f32_16x16x32_bf16 v[104:107], v[176:179], v[200:203], v[104:107]
	s_add_u32 s19, s19, s0
	v_mfma_f32_16x16x32_bf16 v[100:103], v[184:187], v[200:203], v[100:103]
	s_addc_u32 s21, s21, 0
	v_mfma_f32_16x16x32_bf16 v[88:91], v[176:179], v[208:211], v[88:91]
	s_cmp_eq_u32 s96, s38
	v_mfma_f32_16x16x32_bf16 v[82:85], v[184:187], v[208:211], v[84:87]
	s_cselect_b32 s0, s60, s12
	v_mfma_f32_16x16x32_bf16 v[68:71], v[176:179], v[216:219], v[68:71]
	s_cselect_b32 s1, s61, s18
	v_mfma_f32_16x16x32_bf16 v[64:67], v[184:187], v[216:219], v[64:67]
	s_cselect_b32 s64, s62, s19
	v_mfma_f32_16x16x32_bf16 v[120:123], v[180:183], v[196:199], v[120:123]
	s_cselect_b32 s65, s63, s21
	v_mfma_f32_16x16x32_bf16 v[116:119], v[188:191], v[196:199], v[116:119]
	v_mfma_f32_16x16x32_bf16 v[104:107], v[180:183], v[204:207], v[104:107]
	v_mfma_f32_16x16x32_bf16 v[100:103], v[188:191], v[204:207], v[100:103]
	v_mfma_f32_16x16x32_bf16 v[88:91], v[180:183], v[212:215], v[88:91]
	v_mfma_f32_16x16x32_bf16 v[82:85], v[188:191], v[212:215], v[82:85]
	v_mfma_f32_16x16x32_bf16 v[68:71], v[180:183], v[220:223], v[68:71]
	v_mfma_f32_16x16x32_bf16 v[64:67], v[188:191], v[220:223], v[64:67]
	s_setprio 0
	s_barrier
	s_add_i32 s12, s91, s78
	s_mov_b32 m0, s12
	ds_read_b128 v[192:195], v174 offset:16384
	ds_read_b128 v[196:199], v174 offset:17408
	ds_read_b128 v[200:203], v174 offset:18432
	ds_read_b128 v[204:207], v174 offset:19456
	ds_read_b128 v[208:211], v174 offset:20480
	ds_read_b128 v[212:215], v174 offset:21504
	ds_read_b128 v[216:219], v174 offset:22528
	ds_read_b128 v[220:223], v174 offset:23552
	global_load_lds_dwordx4 v152, s[64:65]
	s_add_i32 m0, s12, 0x2000
	s_add_u32 s18, s64, s77
	s_addc_u32 s19, s65, 0
	s_add_i32 s12, s20, s78
	global_load_lds_dwordx4 v156, s[64:65]
	s_mov_b32 m0, s12
	s_nop 0
	global_load_lds_dwordx4 v152, s[18:19]
	s_add_i32 m0, s12, 0x2000
	s_nop 0
	global_load_lds_dwordx4 v156, s[18:19]
	s_mov_b32 m0, s79
	s_nop 0
	global_load_lds_dwordx4 v150, s[0:1]
	s_mov_b32 m0, s80
	s_nop 0
	global_load_lds_dwordx4 v154, s[0:1]
	s_waitcnt vmcnt(8) lgkmcnt(0)
	s_barrier
	s_setprio 1
	v_mfma_f32_16x16x32_bf16 v[60:63], v[132:135], v[192:195], v[60:63]
	v_mfma_f32_16x16x32_bf16 v[56:59], v[142:145], v[192:195], v[56:59]
	v_mfma_f32_16x16x32_bf16 v[44:47], v[132:135], v[200:203], v[44:47]
	v_mfma_f32_16x16x32_bf16 v[40:43], v[142:145], v[200:203], v[40:43]
	v_mfma_f32_16x16x32_bf16 v[28:31], v[132:135], v[208:211], v[28:31]
	v_mfma_f32_16x16x32_bf16 v[24:27], v[142:145], v[208:211], v[24:27]
	v_mfma_f32_16x16x32_bf16 v[12:15], v[132:135], v[216:219], v[12:15]
	v_mfma_f32_16x16x32_bf16 v[8:11], v[142:145], v[216:219], v[8:11]
	v_mfma_f32_16x16x32_bf16 v[60:63], v[136:139], v[196:199], v[60:63]
	v_mfma_f32_16x16x32_bf16 v[56:59], v[158:161], v[196:199], v[56:59]
	v_mfma_f32_16x16x32_bf16 v[44:47], v[136:139], v[204:207], v[44:47]
	v_mfma_f32_16x16x32_bf16 v[40:43], v[158:161], v[204:207], v[40:43]
	v_mfma_f32_16x16x32_bf16 v[28:31], v[136:139], v[212:215], v[28:31]
	v_mfma_f32_16x16x32_bf16 v[24:27], v[158:161], v[212:215], v[24:27]
	v_mfma_f32_16x16x32_bf16 v[12:15], v[136:139], v[220:223], v[12:15]
	v_mfma_f32_16x16x32_bf16 v[8:11], v[158:161], v[220:223], v[8:11]
	v_mfma_f32_16x16x32_bf16 v[52:55], v[176:179], v[192:195], v[52:55]
	v_mfma_f32_16x16x32_bf16 v[48:51], v[184:187], v[192:195], v[48:51]
	v_mfma_f32_16x16x32_bf16 v[36:39], v[176:179], v[200:203], v[36:39]
	v_mfma_f32_16x16x32_bf16 v[32:35], v[184:187], v[200:203], v[32:35]
	v_mfma_f32_16x16x32_bf16 v[20:23], v[176:179], v[208:211], v[20:23]
	v_mfma_f32_16x16x32_bf16 v[16:19], v[184:187], v[208:211], v[16:19]
	v_mfma_f32_16x16x32_bf16 v[4:7], v[176:179], v[216:219], v[4:7]
	v_mfma_f32_16x16x32_bf16 v[0:3], v[184:187], v[216:219], v[0:3]
	v_mfma_f32_16x16x32_bf16 v[52:55], v[180:183], v[196:199], v[52:55]
	v_mfma_f32_16x16x32_bf16 v[48:51], v[188:191], v[196:199], v[48:51]
	v_mfma_f32_16x16x32_bf16 v[36:39], v[180:183], v[204:207], v[36:39]
	v_mfma_f32_16x16x32_bf16 v[32:35], v[188:191], v[204:207], v[32:35]
	v_mfma_f32_16x16x32_bf16 v[20:23], v[180:183], v[212:215], v[20:23]
	v_mfma_f32_16x16x32_bf16 v[16:19], v[188:191], v[212:215], v[16:19]
	v_mfma_f32_16x16x32_bf16 v[4:7], v[180:183], v[220:223], v[4:7]
	v_mfma_f32_16x16x32_bf16 v[0:3], v[188:191], v[220:223], v[0:3]
	s_setprio 0
	s_barrier
; #define PG8_STAGE(bufoff, gbase, voff) do { _Pragma("unroll") for (int _i = 0; _i < 2; ++_i) \
;         __builtin_amdgcn_global_load_lds((const unsigned*)((const char*)(gbase) + (voff)[_i]), (LAS unsigned*)(lds + (bufoff) + ldsw + _i * 8192), 16, 0, 0); } while (0)
; #define PG8_LDA(dst, b, h) do { _Pragma("unroll") for (int m = 0; m < 4; ++m) _Pragma("unroll") for (int k = 0; k < 2; ++k) dst[m][k] = *(const LAS bf16x8*)(lds + PG8_SA(b, h) + aoff + m * 2048 + k * 1024); } while (0)
; #define PG8_LDB(dst, b, h) do { _Pragma("unroll") for (int n = 0; n < 2; ++n) _Pragma("unroll") for (int k = 0; k < 2; ++k) dst[n][k] = *(const LAS bf16x8*)(lds + PG8_SB(b, h) + boff + n * 2048 + k * 1024); } while (0)
; #define PG8_MMA(ai, bj, At, Bt) do { __builtin_amdgcn_s_setprio(1); _Pragma("unroll") for (int m = 0; m < 4; ++m) _Pragma("unroll") for (int n = 0; n < 2; ++n) _Pragma("unroll") for (int k = 0; k < 2; ++k) \
;         acc[ai][bj][m][n] = __builtin_amdgcn_mfma_f32_16x16x32_bf16(Bt[n][k], At[m][k], acc[ai][bj][m][n], 0, 0, 0); __builtin_amdgcn_s_setprio(0); } while (0)
; #define PG8_WAIT_V(n) asm volatile("s_waitcnt vmcnt(" #n ")" ::: "memory")
; #define PG8_WAIT_L(n) asm volatile("s_waitcnt lgkmcnt(" #n ")" ::: "memory")
; #define PG8_BAR __builtin_amdgcn_s_barrier()
; #define PG8_SCHED __builtin_amdgcn_sched_barrier(0)
; DI void gemm_phase(LAS unsigned char* lds, int ph, unsigned char* ws, unsigned char* wg, int l, const float* pscale, int G, int cidx, int nx) {
;     ...
;             PG8_LDB(B0, 1, 0); PG8_LDB(B1, 1, 1); PG8_SCHED; PG8_LDA(At, 1, 0); PG8_STAGE(PG8_SA(0, 1), a2 + hstepA, voffA);
;             PG8_WAIT_V(8); PG8_WAIT_L(0); PG8_BAR; PG8_MMA(0, 0, At, B0); PG8_MMA(0, 1, At, B1); PG8_BAR; PG8_SCHED;
;             PG8_LDA(At, 1, 1); PG8_STAGE(PG8_SB(1, 0), b3, voffB); PG8_STAGE(PG8_SB(1, 1), b3 + hstepB, voffB); PG8_STAGE(PG8_SA(1, 0), a3, voffA);
;             PG8_WAIT_V(8); PG8_WAIT_L(0); PG8_BAR; PG8_MMA(1, 0, At, B0); PG8_MMA(1, 1, At, B1); PG8_BAR; PG8_SCHED;
	s_add_i32 s12, 0, 0x18000
	v_add_u32_e32 v80, s12, v173
	s_add_i32 s18, 0, 0x1c000
	ds_read_b128 v[132:135], v80
	ds_read_b128 v[136:139], v80 offset:1024
	ds_read_b128 v[142:145], v80 offset:2048
	ds_read_b128 v[158:161], v80 offset:3072
	v_add_u32_e32 v80, s18, v173
	ds_read_b128 v[176:179], v80
	ds_read_b128 v[180:183], v80 offset:1024
	ds_read_b128 v[184:187], v80 offset:2048
	ds_read_b128 v[188:191], v80 offset:3072
	s_add_u32 s0, s0, s7
	s_addc_u32 s1, s1, 0
	s_mov_b32 m0, s81
	ds_read_b128 v[192:195], v174 offset:32768
	ds_read_b128 v[196:199], v174 offset:33792
	ds_read_b128 v[200:203], v174 offset:34816
	ds_read_b128 v[204:207], v174 offset:35840
	ds_read_b128 v[208:211], v174 offset:36864
	ds_read_b128 v[212:215], v174 offset:37888
	ds_read_b128 v[216:219], v174 offset:38912
	ds_read_b128 v[220:223], v174 offset:39936
	global_load_lds_dwordx4 v150, s[0:1]
	s_mov_b32 m0, s82
	s_nop 0
	global_load_lds_dwordx4 v154, s[0:1]
	s_waitcnt vmcnt(8) lgkmcnt(0)
	s_barrier
	s_setprio 1
	v_mfma_f32_16x16x32_bf16 v[128:131], v[132:135], v[192:195], v[128:131]
	s_sub_u32 s20, s0, s7
	v_mfma_f32_16x16x32_bf16 v[124:127], v[142:145], v[192:195], v[124:127]
	s_subb_u32 s21, s1, 0
	v_mfma_f32_16x16x32_bf16 v[112:115], v[132:135], v[200:203], v[112:115]
	s_add_u32 s20, s20, s4
	v_mfma_f32_16x16x32_bf16 v[108:111], v[142:145], v[200:203], v[108:111]
	s_addc_u32 s21, s21, s5
	v_mfma_f32_16x16x32_bf16 v[96:99], v[132:135], v[208:211], v[96:99]
	s_add_u32 s0, s64, s4
	v_mfma_f32_16x16x32_bf16 v[92:95], v[142:145], v[208:211], v[92:95]
	s_addc_u32 s1, s65, s5
	v_mfma_f32_16x16x32_bf16 v[76:79], v[132:135], v[216:219], v[76:79]
	v_mfma_f32_16x16x32_bf16 v[72:75], v[142:145], v[216:219], v[72:75]
	v_mfma_f32_16x16x32_bf16 v[128:131], v[136:139], v[196:199], v[128:131]
	v_mfma_f32_16x16x32_bf16 v[124:127], v[158:161], v[196:199], v[124:127]
	v_mfma_f32_16x16x32_bf16 v[112:115], v[136:139], v[204:207], v[112:115]
	v_mfma_f32_16x16x32_bf16 v[108:111], v[158:161], v[204:207], v[108:111]
	v_mfma_f32_16x16x32_bf16 v[96:99], v[136:139], v[212:215], v[96:99]
	v_mfma_f32_16x16x32_bf16 v[92:95], v[158:161], v[212:215], v[92:95]
	v_mfma_f32_16x16x32_bf16 v[76:79], v[136:139], v[220:223], v[76:79]
	v_mfma_f32_16x16x32_bf16 v[72:75], v[158:161], v[220:223], v[72:75]
	v_mfma_f32_16x16x32_bf16 v[120:123], v[176:179], v[192:195], v[120:123]
	v_mfma_f32_16x16x32_bf16 v[116:119], v[184:187], v[192:195], v[116:119]
	v_mfma_f32_16x16x32_bf16 v[104:107], v[176:179], v[200:203], v[104:107]
	v_mfma_f32_16x16x32_bf16 v[100:103], v[184:187], v[200:203], v[100:103]
	v_mfma_f32_16x16x32_bf16 v[86:89], v[176:179], v[208:211], v[88:91]
	v_mfma_f32_16x16x32_bf16 v[82:85], v[184:187], v[208:211], v[82:85]
	v_mfma_f32_16x16x32_bf16 v[68:71], v[176:179], v[216:219], v[68:71]
	v_mfma_f32_16x16x32_bf16 v[64:67], v[184:187], v[216:219], v[64:67]
	v_mfma_f32_16x16x32_bf16 v[120:123], v[180:183], v[196:199], v[120:123]
	v_mfma_f32_16x16x32_bf16 v[116:119], v[188:191], v[196:199], v[116:119]
	v_mfma_f32_16x16x32_bf16 v[104:107], v[180:183], v[204:207], v[104:107]
	v_mfma_f32_16x16x32_bf16 v[100:103], v[188:191], v[204:207], v[100:103]
	v_mfma_f32_16x16x32_bf16 v[88:91], v[180:183], v[212:215], v[86:89]
	v_mfma_f32_16x16x32_bf16 v[84:87], v[188:191], v[212:215], v[82:85]
	v_mfma_f32_16x16x32_bf16 v[68:71], v[180:183], v[220:223], v[68:71]
	v_mfma_f32_16x16x32_bf16 v[64:67], v[188:191], v[220:223], v[64:67]
	s_setprio 0
	s_barrier
	s_add_i32 s19, s12, s78
	s_mov_b32 m0, s19
	ds_read_b128 v[192:195], v174 offset:49152
	ds_read_b128 v[196:199], v174 offset:50176
	ds_read_b128 v[200:203], v174 offset:51200
	ds_read_b128 v[204:207], v174 offset:52224
	ds_read_b128 v[208:211], v174 offset:53248
	ds_read_b128 v[212:215], v174 offset:54272
	ds_read_b128 v[216:219], v174 offset:55296
	ds_read_b128 v[220:223], v174 offset:56320
	global_load_lds_dwordx4 v152, s[0:1]
	s_add_i32 m0, s19, 0x2000
	s_add_i32 s19, s18, s78
	global_load_lds_dwordx4 v156, s[0:1]
	s_add_u32 s0, s0, s77
	s_addc_u32 s1, s1, 0
	s_mov_b32 m0, s19
	s_nop 0
	global_load_lds_dwordx4 v152, s[0:1]
	s_add_i32 m0, s19, 0x2000
	s_nop 0
	global_load_lds_dwordx4 v156, s[0:1]
	s_mov_b32 m0, s93
	s_nop 0
	global_load_lds_dwordx4 v150, s[20:21]
	s_mov_b32 m0, s94
	s_nop 0
	global_load_lds_dwordx4 v154, s[20:21]
	s_waitcnt vmcnt(8) lgkmcnt(0)
	s_barrier
	s_setprio 1
	v_mfma_f32_16x16x32_bf16 v[60:63], v[132:135], v[192:195], v[60:63]
	s_add_i32 s38, s38, 2
	v_mfma_f32_16x16x32_bf16 v[56:59], v[142:145], v[192:195], v[56:59]
	s_cmp_ge_u32 s38, s75
	v_mfma_f32_16x16x32_bf16 v[44:47], v[132:135], v[200:203], v[44:47]
	v_mfma_f32_16x16x32_bf16 v[40:43], v[142:145], v[200:203], v[40:43]
	v_mfma_f32_16x16x32_bf16 v[28:31], v[132:135], v[208:211], v[28:31]
	v_mfma_f32_16x16x32_bf16 v[24:27], v[142:145], v[208:211], v[24:27]
	v_mfma_f32_16x16x32_bf16 v[12:15], v[132:135], v[216:219], v[12:15]
	v_mfma_f32_16x16x32_bf16 v[8:11], v[142:145], v[216:219], v[8:11]
	v_mfma_f32_16x16x32_bf16 v[60:63], v[136:139], v[196:199], v[60:63]
	v_mfma_f32_16x16x32_bf16 v[56:59], v[158:161], v[196:199], v[56:59]
	v_mfma_f32_16x16x32_bf16 v[44:47], v[136:139], v[204:207], v[44:47]
	v_mfma_f32_16x16x32_bf16 v[40:43], v[158:161], v[204:207], v[40:43]
	v_mfma_f32_16x16x32_bf16 v[28:31], v[136:139], v[212:215], v[28:31]
	v_mfma_f32_16x16x32_bf16 v[24:27], v[158:161], v[212:215], v[24:27]
	v_mfma_f32_16x16x32_bf16 v[12:15], v[136:139], v[220:223], v[12:15]
	v_mfma_f32_16x16x32_bf16 v[8:11], v[158:161], v[220:223], v[8:11]
	v_mfma_f32_16x16x32_bf16 v[52:55], v[176:179], v[192:195], v[52:55]
	v_mfma_f32_16x16x32_bf16 v[48:51], v[184:187], v[192:195], v[48:51]
	v_mfma_f32_16x16x32_bf16 v[36:39], v[176:179], v[200:203], v[36:39]
	v_mfma_f32_16x16x32_bf16 v[32:35], v[184:187], v[200:203], v[32:35]
	v_mfma_f32_16x16x32_bf16 v[20:23], v[176:179], v[208:211], v[20:23]
	v_mfma_f32_16x16x32_bf16 v[16:19], v[184:187], v[208:211], v[16:19]
	v_mfma_f32_16x16x32_bf16 v[4:7], v[176:179], v[216:219], v[4:7]
	v_mfma_f32_16x16x32_bf16 v[0:3], v[184:187], v[216:219], v[0:3]
	v_mfma_f32_16x16x32_bf16 v[52:55], v[180:183], v[196:199], v[52:55]
	v_mfma_f32_16x16x32_bf16 v[48:51], v[188:191], v[196:199], v[48:51]
	v_mfma_f32_16x16x32_bf16 v[36:39], v[180:183], v[204:207], v[36:39]
	v_mfma_f32_16x16x32_bf16 v[32:35], v[188:191], v[204:207], v[32:35]
	v_mfma_f32_16x16x32_bf16 v[20:23], v[180:183], v[212:215], v[20:23]
	v_mfma_f32_16x16x32_bf16 v[16:19], v[188:191], v[212:215], v[16:19]
	v_mfma_f32_16x16x32_bf16 v[4:7], v[180:183], v[220:223], v[4:7]
	v_mfma_f32_16x16x32_bf16 v[0:3], v[188:191], v[220:223], v[0:3]
	s_setprio 0
	s_barrier
	s_cbranch_scc1 .LBB0_507
